# neighbour-team overlap check deferred to just before the first store of the phase (every wave polls up to four team counters)
# speedup vs baseline: 1.0113x; 1.0113x over previous
.LBB0_173:
	s_cmp_lg_u32 s46, 1
	s_cbranch_scc1 .Lnb0_done
	s_cmpk_lg_u32 s98, 0x100
	s_cbranch_scc1 .Lnb0_done
	v_readlane_b32 s1, v243, 19
	s_mov_b32 s34, 0
	s_cmp_eq_u32 s1, 3
	s_cselect_b32 s34, 9, s34
	s_cselect_b32 s35, 5958, s35
	s_cmp_eq_u32 s1, 6
	s_cselect_b32 s34, 4, s34
	s_cselect_b32 s35, 7282, s35
	s_cmp_eq_u32 s1, 9
	s_cselect_b32 s34, 11, s34
	s_cselect_b32 s35, 16384, s35
	s_cmp_eq_u32 s1, 13
	s_cselect_b32 s34, 12, s34
	s_cselect_b32 s35, 5958, s35
	s_cmp_eq_u32 s1, 16
	s_cselect_b32 s34, 4, s34
	s_cselect_b32 s35, 5462, s35
	s_cmp_eq_u32 s1, 19
	s_cselect_b32 s34, 11, s34
	s_cselect_b32 s35, 16384, s35
	s_cmp_eq_u32 s34, 0
	s_cbranch_scc1 .Lnb0_done
	v_readlane_b32 s1, v243, 16
	s_and_b32 vcc_lo, s1, 7
	s_lshl_b32 vcc_lo, vcc_lo, 3
	s_bfe_u32 vcc_hi, s1, 0x30003
	s_add_i32 vcc_lo, vcc_lo, vcc_hi
	s_mul_i32 vcc_hi, vcc_lo, s34
	s_add_i32 s1, vcc_hi, s34
	s_add_i32 s1, s1, -1
	s_mul_i32 vcc_hi, vcc_hi, s35
	s_lshr_b32 vcc_hi, vcc_hi, 16
	s_mul_i32 s1, s1, s35
	s_lshr_b32 s1, s1, 16
	s_min_u32 s1, s1, 63
	s_cmp_gt_u32 vcc_hi, s1
	s_cbranch_scc1 .Lnb0_done
	s_min_u32 s34, vcc_hi, s1
	s_lshr_b32 s35, s34, 3
	s_and_b32 s34, s34, 7
	s_lshl_b32 s34, s34, 3
	s_add_i32 s34, s34, s35
	s_lshl_b32 s34, s34, 5
	v_mov_b32_e32 v244, s34
	s_add_i32 vcc_hi, vcc_hi, 1
	s_min_u32 s34, vcc_hi, s1
	s_lshr_b32 s35, s34, 3
	s_and_b32 s34, s34, 7
	s_lshl_b32 s34, s34, 3
	s_add_i32 s34, s34, s35
	s_lshl_b32 s34, s34, 5
	v_mov_b32_e32 v245, s34
	s_add_i32 vcc_hi, vcc_hi, 1
	s_min_u32 s34, vcc_hi, s1
	s_lshr_b32 s35, s34, 3
	s_and_b32 s34, s34, 7
	s_lshl_b32 s34, s34, 3
	s_add_i32 s34, s34, s35
	s_lshl_b32 s34, s34, 5
	v_mov_b32_e32 v246, s34
	s_add_i32 vcc_hi, vcc_hi, 1
	s_min_u32 s34, vcc_hi, s1
	s_lshr_b32 s35, s34, 3
	s_and_b32 s34, s34, 7
	s_lshl_b32 s34, s34, 3
	s_add_i32 s34, s34, s35
	s_lshl_b32 s34, s34, 5
	v_mov_b32_e32 v247, s34
	s_add_i32 vcc_hi, vcc_hi, 1
	s_add_u32 s34, s96, 0xeb12d00
	s_addc_u32 s35, s97, 0
	v_readlane_b32 s1, v243, 60
	s_lshl_b32 s1, s1, 2
.Lnb0_poll:
	global_load_dword v240, v244, s[34:35] sc1
	global_load_dword v241, v245, s[34:35] sc1
	global_load_dword v242, v246, s[34:35] sc1
	global_load_dword v251, v247, s[34:35] sc1
	s_waitcnt vmcnt(0)
	v_min_u32_e32 v240, v240, v241
	v_min_u32_e32 v242, v242, v251
	v_min_u32_e32 v240, v240, v242
	s_nop 0
	v_readfirstlane_b32 s0, v240
	s_cmp_ge_u32 s0, s1
	s_cbranch_scc1 .Lnb0_done
	s_sleep 1
	s_branch .Lnb0_poll

.LBB0_175:
	s_cmp_lg_u32 s70, 1
	s_cbranch_scc0 .LBB0_183
	s_cmp_lg_u32 s46, 1
	s_cbranch_scc1 .Lnb2_done
	s_cmpk_lg_u32 s98, 0x100
	s_cbranch_scc1 .Lnb2_done
	v_readlane_b32 s1, v243, 19
	s_mov_b32 s34, 0
	s_cmp_eq_u32 s1, 3
	s_cselect_b32 s34, 9, s34
	s_cselect_b32 s35, 5958, s35
	s_cmp_eq_u32 s1, 6
	s_cselect_b32 s34, 4, s34
	s_cselect_b32 s35, 7282, s35
	s_cmp_eq_u32 s1, 9
	s_cselect_b32 s34, 11, s34
	s_cselect_b32 s35, 16384, s35
	s_cmp_eq_u32 s1, 13
	s_cselect_b32 s34, 12, s34
	s_cselect_b32 s35, 5958, s35
	s_cmp_eq_u32 s1, 16
	s_cselect_b32 s34, 4, s34
	s_cselect_b32 s35, 5462, s35
	s_cmp_eq_u32 s1, 19
	s_cselect_b32 s34, 11, s34
	s_cselect_b32 s35, 16384, s35
	s_cmp_eq_u32 s34, 0
	s_cbranch_scc1 .Lnb2_done
	v_readlane_b32 s1, v243, 16
	s_and_b32 vcc_lo, s1, 7
	s_lshl_b32 vcc_lo, vcc_lo, 3
	s_bfe_u32 vcc_hi, s1, 0x30003
	s_add_i32 vcc_lo, vcc_lo, vcc_hi
	s_mul_i32 vcc_hi, vcc_lo, s34
	s_add_i32 s1, vcc_hi, s34
	s_add_i32 s1, s1, -1
	s_mul_i32 vcc_hi, vcc_hi, s35
	s_lshr_b32 vcc_hi, vcc_hi, 16
	s_mul_i32 s1, s1, s35
	s_lshr_b32 s1, s1, 16
	s_min_u32 s1, s1, 63
	s_cmp_gt_u32 vcc_hi, s1
	s_cbranch_scc1 .Lnb2_done
	s_min_u32 s34, vcc_hi, s1
	s_lshr_b32 s35, s34, 3
	s_and_b32 s34, s34, 7
	s_lshl_b32 s34, s34, 3
	s_add_i32 s34, s34, s35
	s_lshl_b32 s34, s34, 5
	v_mov_b32_e32 v244, s34
	s_add_i32 vcc_hi, vcc_hi, 1
	s_min_u32 s34, vcc_hi, s1
	s_lshr_b32 s35, s34, 3
	s_and_b32 s34, s34, 7
	s_lshl_b32 s34, s34, 3
	s_add_i32 s34, s34, s35
	s_lshl_b32 s34, s34, 5
	v_mov_b32_e32 v245, s34
	s_add_i32 vcc_hi, vcc_hi, 1
	s_min_u32 s34, vcc_hi, s1
	s_lshr_b32 s35, s34, 3
	s_and_b32 s34, s34, 7
	s_lshl_b32 s34, s34, 3
	s_add_i32 s34, s34, s35
	s_lshl_b32 s34, s34, 5
	v_mov_b32_e32 v246, s34
	s_add_i32 vcc_hi, vcc_hi, 1
	s_min_u32 s34, vcc_hi, s1
	s_lshr_b32 s35, s34, 3
	s_and_b32 s34, s34, 7
	s_lshl_b32 s34, s34, 3
	s_add_i32 s34, s34, s35
	s_lshl_b32 s34, s34, 5
	v_mov_b32_e32 v247, s34
	s_add_i32 vcc_hi, vcc_hi, 1
	s_add_u32 s34, s96, 0xeb12d00
	s_addc_u32 s35, s97, 0
	v_readlane_b32 s1, v243, 60
	s_lshl_b32 s1, s1, 2

.Lnb2_done:
	s_lshl_b32 s0, s88, 8
	v_readlane_b32 s1, v243, 52
	s_or_b32 s80, s0, s1
	v_readlane_b32 s0, v243, 40
	s_cmp_lt_i32 s80, s0
	v_readlane_b32 s34, v243, 32
	s_cselect_b64 s[0:1], -1, 0
	s_cmp_ge_i32 s80, s34
	s_cselect_b64 s[34:35], -1, 0
	s_and_b64 s[0:1], s[34:35], s[0:1]
	s_and_b64 s[0:1], s[0:1], exec
	v_readlane_b32 s1, v243, 26
	s_cselect_b32 s0, 2, 0
	s_cmp_ge_i32 s80, s1
	s_cselect_b32 s0, s0, 1
	s_cmp_lt_i32 s0, 1
	s_mov_b64 s[34:35], -1
	s_cbranch_scc1 .LBB0_180
	s_cmp_eq_u32 s0, 1
	s_mov_b64 s[34:35], s[72:73]
	s_cbranch_scc1 .LBB0_179
	v_readlane_b32 s34, v243, 42
	v_readlane_b32 s35, v243, 43

.LBB0_404:
	v_readlane_b32 s0, v243, 19
	v_readlane_b32 s22, v243, 20
	s_cmp_lg_u32 s0, 20
	s_mul_hi_u32 s16, s22, 0xcccccccd
	s_cselect_b64 s[0:1], -1, 0
	s_lshr_b32 s16, s16, 3
	s_mul_i32 s16, s16, 10
	s_sub_i32 s16, s22, s16
	s_cmp_lg_u32 s16, 6
	s_cselect_b64 s[22:23], -1, 0
	s_and_b64 s[0:1], s[0:1], s[22:23]
	s_andn2_b64 vcc, exec, s[0:1]
	s_cbranch_vccnz .LBB0_8
	s_waitcnt vmcnt(0)
	s_waitcnt vmcnt(0) lgkmcnt(0)
	s_barrier
	s_cmpk_lg_u32 s98, 0x100
	s_cbranch_scc1 .Ltb_cnt_done
	v_readlane_b32 s0, v243, 19
	s_mov_b32 s1, 0xc9f24
	s_lshr_b32 s1, s1, s0
	s_and_b32 s1, s1, 1
	s_cmp_eq_u32 s1, 0
	s_cbranch_scc1 .Ltb_cnt_done
	v_readlane_b32 s0, v243, 60
	s_add_i32 s0, s0, 1
	s_nop 0
	v_writelane_b32 v243, s0, 60
.Ltb_cnt_done:
	s_and_saveexec_b64 s[22:23], s[84:85]
	s_cbranch_execz .LBB0_7
	s_cmpk_lg_u32 s98, 0x100
	s_cbranch_scc1 .Ltb_full
	v_readlane_b32 s0, v243, 19
	s_mov_b32 s1, 0xc9f24
	s_lshr_b32 s1, s1, s0
	s_and_b32 s1, s1, 1
	s_cmp_eq_u32 s1, 0
	s_cbranch_scc1 .Ltb_full
	v_readlane_b32 s0, v243, 16
	s_and_b32 s0, s0, 63
	s_lshl_b32 s0, s0, 5
	s_add_u32 s28, s96, 0xeb12d00
	s_addc_u32 s29, s97, 0
	s_add_u32 s28, s28, s0
	s_addc_u32 s29, s29, 0
	v_mov_b32_e32 v1, 1
	global_atomic_add v0, v1, s[28:29]
	buffer_inv sc1
	v_readlane_b32 s0, v243, 60
	s_lshl_b32 s0, s0, 2
.Ltb_wait:
	global_load_dword v2, v0, s[28:29] sc1
	s_waitcnt vmcnt(0)
	v_readfirstlane_b32 s1, v2
	s_cmp_ge_u32 s1, s0
	s_cbranch_scc1 .LBB0_7
	s_sleep 1
	s_branch .Ltb_wait
.Ltb_full:
	v_readlane_b32 s0, v248, 61
	s_waitcnt vmcnt(0) expcnt(0) lgkmcnt(0)
	s_nop 0
	v_mov_b32_e32 v1, s0
	ds_read_b32 v3, v1
	v_readlane_b32 s0, v248, 62
	s_waitcnt lgkmcnt(0)
	v_cmp_ne_u32_e32 vcc, 0, v3
	v_mov_b32_e32 v1, s0
	ds_read_b32 v2, v1
	s_cbranch_vccnz .LBB0_421
	s_mov_b32 s0, 1
	s_branch .LBB0_409

	.amdhsa_kernel _Z14fwd_megakernel6Params
		.amdhsa_group_segment_fixed_size 0
		.amdhsa_private_segment_fixed_size 0
		.amdhsa_kernarg_size 472
		.amdhsa_user_sgpr_count 2
		.amdhsa_user_sgpr_dispatch_ptr 0
		.amdhsa_user_sgpr_queue_ptr 0
		.amdhsa_user_sgpr_kernarg_segment_ptr 1
		.amdhsa_user_sgpr_dispatch_id 0
		.amdhsa_user_sgpr_kernarg_preload_length 0
		.amdhsa_user_sgpr_kernarg_preload_offset 0
		.amdhsa_user_sgpr_private_segment_size 0
		.amdhsa_uses_dynamic_stack 0
		.amdhsa_enable_private_segment 0
		.amdhsa_system_sgpr_workgroup_id_x 1
		.amdhsa_system_sgpr_workgroup_id_y 0
		.amdhsa_system_sgpr_workgroup_id_z 0
		.amdhsa_system_sgpr_workgroup_info 0
		.amdhsa_system_vgpr_workitem_id 2
		.amdhsa_next_free_vgpr 252
		.amdhsa_next_free_sgpr 102
		.amdhsa_accum_offset 252
		.amdhsa_reserve_vcc 1
		.amdhsa_float_round_mode_32 0
		.amdhsa_float_round_mode_16_64 0
		.amdhsa_float_denorm_mode_32 3
		.amdhsa_float_denorm_mode_16_64 3
		.amdhsa_dx10_clamp 1
		.amdhsa_ieee_mode 1
		.amdhsa_fp16_overflow 0
		.amdhsa_tg_split 0
		.amdhsa_exception_fp_ieee_invalid_op 0
		.amdhsa_exception_fp_denorm_src 0
		.amdhsa_exception_fp_ieee_div_zero 0
		.amdhsa_exception_fp_ieee_overflow 0
		.amdhsa_exception_fp_ieee_underflow 0
		.amdhsa_exception_fp_ieee_inexact 0
		.amdhsa_exception_int_div_zero 0
	.end_amdhsa_kernel

amdhsa.kernels:
  - .agpr_count:     0
    .args:
      - .offset:         0
        .size:           216
        .value_kind:     by_value
      - .offset:         216
        .size:           4
        .value_kind:     hidden_block_count_x
      - .offset:         220
        .size:           4
        .value_kind:     hidden_block_count_y
      - .offset:         224
        .size:           4
        .value_kind:     hidden_block_count_z
      - .offset:         228
        .size:           2
        .value_kind:     hidden_group_size_x
      - .offset:         230
        .size:           2
        .value_kind:     hidden_group_size_y
      - .offset:         232
        .size:           2
        .value_kind:     hidden_group_size_z
      - .offset:         234
        .size:           2
        .value_kind:     hidden_remainder_x
      - .offset:         236
        .size:           2
        .value_kind:     hidden_remainder_y
      - .offset:         238
        .size:           2
        .value_kind:     hidden_remainder_z
      - .offset:         256
        .size:           8
        .value_kind:     hidden_global_offset_x
      - .offset:         264
        .size:           8
        .value_kind:     hidden_global_offset_y
      - .offset:         272
        .size:           8
        .value_kind:     hidden_global_offset_z
      - .offset:         280
        .size:           2
        .value_kind:     hidden_grid_dims
      - .offset:         304
        .size:           8
        .value_kind:     hidden_multigrid_sync_arg
      - .offset:         336
        .size:           4
        .value_kind:     hidden_dynamic_lds_size
    .group_segment_fixed_size: 0
    .kernarg_segment_align: 8
    .kernarg_segment_size: 472
    .language:       OpenCL C
    .language_version:
      - 2
      - 0
    .max_flat_workgroup_size: 512
    .name:           _Z14fwd_megakernel6Params
    .private_segment_fixed_size: 0
    .sgpr_count: 108
    .sgpr_spill_count: 289
    .symbol:         _Z14fwd_megakernel6Params.kd
    .uniform_work_group_size: 1
    .uses_dynamic_stack: false
    .vgpr_count: 252
    .vgpr_spill_count: 0
    .wavefront_size: 64
